# hot MFMA loop headers (GEMM K-loops, attention tile loop) aligned to 64 bytes
# speedup vs baseline: 1.0029x; 1.0029x over previous
.LBB0_364:
	s_andn2_b64 vcc, exec, s[26:27]
	s_cbranch_vccnz .LBB0_372
	s_add_u32 s40, s40, 0x40080
	s_addc_u32 s41, s41, 0
	s_add_u32 s2, s42, 0x100
	s_addc_u32 s3, s43, 0
	s_mov_b32 s12, 0
	v_mov_b32_e32 v0, 0
	v_mov_b32_e32 v1, 0
	v_mov_b32_e32 v2, 0
	v_mov_b32_e32 v3, 0
	v_mov_b32_e32 v8, 0
	v_mov_b32_e32 v9, 0
	v_mov_b32_e32 v10, 0
	v_mov_b32_e32 v11, 0
	v_mov_b32_e32 v16, 0
	v_mov_b32_e32 v17, 0
	v_mov_b32_e32 v18, 0
	v_mov_b32_e32 v19, 0
	v_mov_b32_e32 v24, 0
	v_mov_b32_e32 v25, 0
	v_mov_b32_e32 v26, 0
	v_mov_b32_e32 v27, 0
	v_mov_b32_e32 v32, 0
	v_mov_b32_e32 v33, 0
	v_mov_b32_e32 v34, 0
	v_mov_b32_e32 v35, 0
	v_mov_b32_e32 v40, 0
	v_mov_b32_e32 v41, 0
	v_mov_b32_e32 v42, 0
	v_mov_b32_e32 v43, 0
	v_mov_b32_e32 v48, 0
	v_mov_b32_e32 v49, 0
	v_mov_b32_e32 v50, 0
	v_mov_b32_e32 v51, 0
	v_mov_b32_e32 v56, 0
	v_mov_b32_e32 v57, 0
	v_mov_b32_e32 v58, 0
	v_mov_b32_e32 v59, 0
	v_mov_b32_e32 v4, 0
	v_mov_b32_e32 v5, 0
	v_mov_b32_e32 v6, 0
	v_mov_b32_e32 v7, 0
	v_mov_b32_e32 v12, 0
	v_mov_b32_e32 v13, 0
	v_mov_b32_e32 v14, 0
	v_mov_b32_e32 v15, 0
	v_mov_b32_e32 v20, 0
	v_mov_b32_e32 v21, 0
	v_mov_b32_e32 v22, 0
	v_mov_b32_e32 v23, 0
	v_mov_b32_e32 v28, 0
	v_mov_b32_e32 v29, 0
	v_mov_b32_e32 v30, 0
	v_mov_b32_e32 v31, 0
	v_mov_b32_e32 v36, 0
	v_mov_b32_e32 v37, 0
	v_mov_b32_e32 v38, 0
	v_mov_b32_e32 v39, 0
	v_mov_b32_e32 v44, 0
	v_mov_b32_e32 v45, 0
	v_mov_b32_e32 v46, 0
	v_mov_b32_e32 v47, 0
	v_mov_b32_e32 v52, 0
	v_mov_b32_e32 v53, 0
	v_mov_b32_e32 v54, 0
	v_mov_b32_e32 v55, 0
	v_mov_b32_e32 v60, 0
	v_mov_b32_e32 v61, 0
	v_mov_b32_e32 v62, 0
	v_mov_b32_e32 v63, 0
	v_mov_b32_e32 v64, 0
	v_mov_b32_e32 v65, 0
	v_mov_b32_e32 v66, 0
	v_mov_b32_e32 v67, 0
	v_mov_b32_e32 v72, 0
	v_mov_b32_e32 v73, 0
	v_mov_b32_e32 v74, 0
	v_mov_b32_e32 v75, 0
	v_mov_b32_e32 v80, 0
	v_mov_b32_e32 v81, 0
	v_mov_b32_e32 v82, 0
	v_mov_b32_e32 v83, 0
	v_mov_b32_e32 v88, 0
	v_mov_b32_e32 v89, 0
	v_mov_b32_e32 v90, 0
	v_mov_b32_e32 v91, 0
	v_mov_b32_e32 v96, 0
	v_mov_b32_e32 v97, 0
	v_mov_b32_e32 v98, 0
	v_mov_b32_e32 v99, 0
	v_mov_b32_e32 v104, 0
	v_mov_b32_e32 v105, 0
	v_mov_b32_e32 v106, 0
	v_mov_b32_e32 v107, 0
	v_mov_b32_e32 v128, 0
	v_mov_b32_e32 v129, 0
	v_mov_b32_e32 v130, 0
	v_mov_b32_e32 v131, 0
	v_mov_b32_e32 v136, 0
	v_mov_b32_e32 v137, 0
	v_mov_b32_e32 v138, 0
	v_mov_b32_e32 v139, 0
	v_mov_b32_e32 v68, 0
	v_mov_b32_e32 v69, 0
	v_mov_b32_e32 v70, 0
	v_mov_b32_e32 v71, 0
	v_mov_b32_e32 v76, 0
	v_mov_b32_e32 v77, 0
	v_mov_b32_e32 v78, 0
	v_mov_b32_e32 v79, 0
	v_mov_b32_e32 v84, 0
	v_mov_b32_e32 v85, 0
	v_mov_b32_e32 v86, 0
	v_mov_b32_e32 v87, 0
	v_mov_b32_e32 v92, 0
	v_mov_b32_e32 v93, 0
	v_mov_b32_e32 v94, 0
	v_mov_b32_e32 v95, 0
	v_mov_b32_e32 v100, 0
	v_mov_b32_e32 v101, 0
	v_mov_b32_e32 v102, 0
	v_mov_b32_e32 v103, 0
	v_mov_b32_e32 v108, 0
	v_mov_b32_e32 v109, 0
	v_mov_b32_e32 v110, 0
	v_mov_b32_e32 v111, 0
	v_mov_b32_e32 v132, 0
	v_mov_b32_e32 v133, 0
	v_mov_b32_e32 v134, 0
	v_mov_b32_e32 v135, 0
	v_mov_b32_e32 v140, 0
	v_mov_b32_e32 v141, 0
	v_mov_b32_e32 v142, 0
	v_mov_b32_e32 v143, 0
	.p2alignl 6, 3212836864

.LBB0_383:
	s_lshl_b32 s0, s0, 5
	s_and_b32 s3, s0, 0x60
	s_mov_b64 s[0:1], 0x80
	s_add_i32 m0, s7, 0x18000
	v_lshl_add_u64 v[6:7], v[6:7], 0, s[0:1]
	s_waitcnt vmcnt(2)
	s_barrier
	global_load_lds_dwordx4 v[6:7], off
	v_lshl_add_u64 v[4:5], v[4:5], 0, s[0:1]
	s_add_i32 m0, s7, 0x1a000
	s_add_i32 s17, s7, 0x8000
	s_add_i32 s18, s7, 0xa000
	global_load_lds_dwordx4 v[4:5], off
	v_lshl_add_u64 v[2:3], v[2:3], 0, s[0:1]
	s_mov_b32 m0, s17
	s_add_u32 s24, s20, 0x80080
	global_load_lds_dwordx4 v[2:3], off
	v_lshl_add_u64 v[0:1], v[0:1], 0, s[0:1]
	s_mov_b32 m0, s18
	s_addc_u32 s25, s21, 0
	global_load_lds_dwordx4 v[0:1], off
	s_add_i32 m0, s7, 0x1c000
	v_lshl_add_u64 v[0:1], s[24:25], 0, v[128:129]
	global_load_lds_dwordx4 v[0:1], off
	v_lshl_add_u64 v[0:1], s[24:25], 0, v[134:135]
	s_add_i32 m0, s7, 0x1e000
	v_and_b32_e32 v143, 15, v8
	global_load_lds_dwordx4 v[0:1], off
	v_lshrrev_b32_e32 v8, 1, v8
	s_waitcnt vmcnt(6)
	v_and_b32_e32 v8, 24, v8
	v_lshl_or_b32 v130, s12, 6, v143
	s_mov_b64 s[4:5], 0x80080
	s_cmp_lt_i32 s6, 1
	v_lshlrev_b32_e32 v132, 1, v8
	v_mov_b32_e32 v126, 0
	v_mov_b32_e32 v125, 0
	v_mov_b32_e32 v124, 0
	v_mov_b32_e32 v123, 0
	v_mov_b32_e32 v122, 0
	v_mov_b32_e32 v121, 0
	v_mov_b32_e32 v120, 0
	v_mov_b32_e32 v111, 0
	v_mov_b32_e32 v110, 0
	v_mov_b32_e32 v109, 0
	v_mov_b32_e32 v108, 0
	v_mov_b32_e32 v107, 0
	v_mov_b32_e32 v106, 0
	v_mov_b32_e32 v105, 0
	v_mov_b32_e32 v104, 0
	v_mov_b32_e32 v95, 0
	v_mov_b32_e32 v94, 0
	v_mov_b32_e32 v93, 0
	v_mov_b32_e32 v92, 0
	v_mov_b32_e32 v91, 0
	v_mov_b32_e32 v90, 0
	v_mov_b32_e32 v89, 0
	v_mov_b32_e32 v88, 0
	v_mov_b32_e32 v79, 0
	v_mov_b32_e32 v78, 0
	v_mov_b32_e32 v77, 0
	v_mov_b32_e32 v76, 0
	v_mov_b32_e32 v75, 0
	v_mov_b32_e32 v74, 0
	v_mov_b32_e32 v73, 0
	v_mov_b32_e32 v72, 0
	v_mov_b32_e32 v119, 0
	v_mov_b32_e32 v118, 0
	v_mov_b32_e32 v117, 0
	v_mov_b32_e32 v116, 0
	v_mov_b32_e32 v115, 0
	v_mov_b32_e32 v114, 0
	v_mov_b32_e32 v113, 0
	v_mov_b32_e32 v112, 0
	v_mov_b32_e32 v103, 0
	v_mov_b32_e32 v102, 0
	v_mov_b32_e32 v101, 0
	v_mov_b32_e32 v100, 0
	v_mov_b32_e32 v99, 0
	v_mov_b32_e32 v98, 0
	v_mov_b32_e32 v97, 0
	v_mov_b32_e32 v96, 0
	v_mov_b32_e32 v87, 0
	v_mov_b32_e32 v86, 0
	v_mov_b32_e32 v85, 0
	v_mov_b32_e32 v84, 0
	v_mov_b32_e32 v83, 0
	v_mov_b32_e32 v82, 0
	v_mov_b32_e32 v81, 0
	v_mov_b32_e32 v80, 0
	v_mov_b32_e32 v71, 0
	v_mov_b32_e32 v70, 0
	v_mov_b32_e32 v69, 0
	v_mov_b32_e32 v68, 0
	v_mov_b32_e32 v67, 0
	v_mov_b32_e32 v66, 0
	v_mov_b32_e32 v65, 0
	v_mov_b32_e32 v64, 0
	v_mov_b32_e32 v63, 0
	v_mov_b32_e32 v62, 0
	v_mov_b32_e32 v61, 0
	v_mov_b32_e32 v60, 0
	v_mov_b32_e32 v59, 0
	v_mov_b32_e32 v58, 0
	v_mov_b32_e32 v57, 0
	v_mov_b32_e32 v56, 0
	v_mov_b32_e32 v47, 0
	v_mov_b32_e32 v46, 0
	v_mov_b32_e32 v45, 0
	v_mov_b32_e32 v44, 0
	v_mov_b32_e32 v43, 0
	v_mov_b32_e32 v42, 0
	v_mov_b32_e32 v41, 0
	v_mov_b32_e32 v40, 0
	v_mov_b32_e32 v31, 0
	v_mov_b32_e32 v30, 0
	v_mov_b32_e32 v29, 0
	v_mov_b32_e32 v28, 0
	v_mov_b32_e32 v27, 0
	v_mov_b32_e32 v26, 0
	v_mov_b32_e32 v25, 0
	v_mov_b32_e32 v24, 0
	v_mov_b32_e32 v15, 0
	v_mov_b32_e32 v14, 0
	v_mov_b32_e32 v13, 0
	v_mov_b32_e32 v12, 0
	v_mov_b32_e32 v11, 0
	v_mov_b32_e32 v10, 0
	v_mov_b32_e32 v9, 0
	v_mov_b32_e32 v8, 0
	v_mov_b32_e32 v55, 0
	v_mov_b32_e32 v54, 0
	v_mov_b32_e32 v53, 0
	v_mov_b32_e32 v52, 0
	v_mov_b32_e32 v51, 0
	v_mov_b32_e32 v50, 0
	v_mov_b32_e32 v49, 0
	v_mov_b32_e32 v48, 0
	v_mov_b32_e32 v39, 0
	v_mov_b32_e32 v38, 0
	v_mov_b32_e32 v37, 0
	v_mov_b32_e32 v36, 0
	v_mov_b32_e32 v35, 0
	v_mov_b32_e32 v34, 0
	v_mov_b32_e32 v33, 0
	v_mov_b32_e32 v32, 0
	v_mov_b32_e32 v23, 0
	v_mov_b32_e32 v22, 0
	v_mov_b32_e32 v21, 0
	v_mov_b32_e32 v20, 0
	v_mov_b32_e32 v19, 0
	v_mov_b32_e32 v18, 0
	v_mov_b32_e32 v17, 0
	v_mov_b32_e32 v16, 0
	v_mov_b32_e32 v7, 0
	v_mov_b32_e32 v6, 0
	v_mov_b32_e32 v5, 0
	v_mov_b32_e32 v4, 0
	v_mov_b32_e32 v3, 0
	v_mov_b32_e32 v2, 0
	v_mov_b32_e32 v1, 0
	v_mov_b32_e32 v0, 0
	s_barrier
	s_cbranch_scc1 .LBB0_387
	v_lshlrev_b32_e32 v0, 6, v130
	s_movk_i32 s23, 0x3c0
	v_lshlrev_b32_e32 v1, 2, v130
	v_and_or_b32 v0, v0, s23, v132
	s_lshl_b32 s12, s12, 13
	v_and_b32_e32 v1, 32, v1
	v_bitop3_b32 v2, v0, s12, v1 bitop3:0xde
	v_lshlrev_b32_e32 v1, 2, v143
	v_lshl_or_b32 v0, v143, 6, v132
	s_lshl_b32 s12, s3, 7
	v_and_b32_e32 v1, 32, v1
	v_bitop3_b32 v3, v0, s12, v1 bitop3:0xde
	v_lshlrev_b32_e32 v0, 15, v141
	v_and_b32_e32 v0, 0xffff0000, v0
	v_lshl_add_u32 v0, v140, 12, v0
	v_and_b32_e32 v1, 1, v141
	v_lshl_or_b32 v0, v1, 6, v0
	v_lshl_add_u32 v0, v142, 1, v0
	v_mov_b32_e32 v1, 0
	v_lshl_add_u64 v[140:141], s[10:11], 0, v[0:1]
	v_lshlrev_b32_e32 v0, 15, v127
	v_and_b32_e32 v0, 0xffff0000, v0
	v_lshl_add_u32 v0, v131, 12, v0
	v_and_b32_e32 v4, 1, v127
	v_lshl_or_b32 v0, v4, 6, v0
	s_add_i32 s28, 0, 0x10000
	s_add_i32 s30, 0, 0x14000
	s_add_i32 s33, 0, 0x18000
	s_add_i32 s35, 0, 0x1c000
	v_lshl_add_u32 v0, v133, 1, v0
	v_add_u32_e32 v131, s28, v3
	v_add_u32_e32 v133, s30, v3
	s_add_i32 s28, s28, s22
	s_add_i32 s30, s30, s22
	v_add_u32_e32 v145, s33, v3
	v_add_u32_e32 v146, s35, v3
	s_add_i32 s33, s33, s22
	s_add_i32 s35, s35, s22
	s_add_i32 s19, s6, -2
	v_lshl_add_u64 v[142:143], s[10:11], 0, v[0:1]
	s_mov_b32 s12, 0
	v_add_u32_e32 v144, 0, v2
	s_add_i32 s26, s7, 0xc000
	s_add_i32 s27, s7, 0xe000
	s_add_i32 s29, s28, 0x2000
	s_add_i32 s31, s30, 0x2000
	s_add_i32 s34, s33, 0x2000
	s_add_i32 s36, s35, 0x2000
	v_mov_b32_e32 v0, v1
	v_mov_b32_e32 v2, v1
	v_mov_b32_e32 v3, v1
	v_mov_b32_e32 v4, v1
	v_mov_b32_e32 v5, v1
	v_mov_b32_e32 v6, v1
	v_mov_b32_e32 v7, v1
	v_mov_b32_e32 v16, v1
	v_mov_b32_e32 v17, v1
	v_mov_b32_e32 v18, v1
	v_mov_b32_e32 v19, v1
	v_mov_b32_e32 v20, v1
	v_mov_b32_e32 v21, v1
	v_mov_b32_e32 v22, v1
	v_mov_b32_e32 v23, v1
	v_mov_b32_e32 v32, v1
	v_mov_b32_e32 v33, v1
	v_mov_b32_e32 v34, v1
	v_mov_b32_e32 v35, v1
	v_mov_b32_e32 v36, v1
	v_mov_b32_e32 v37, v1
	v_mov_b32_e32 v38, v1
	v_mov_b32_e32 v39, v1
	v_mov_b32_e32 v48, v1
	v_mov_b32_e32 v49, v1
	v_mov_b32_e32 v50, v1
	v_mov_b32_e32 v51, v1
	v_mov_b32_e32 v52, v1
	v_mov_b32_e32 v53, v1
	v_mov_b32_e32 v54, v1
	v_mov_b32_e32 v55, v1
	v_mov_b32_e32 v8, v1
	v_mov_b32_e32 v9, v1
	v_mov_b32_e32 v10, v1
	v_mov_b32_e32 v11, v1
	v_mov_b32_e32 v12, v1
	v_mov_b32_e32 v13, v1
	v_mov_b32_e32 v14, v1
	v_mov_b32_e32 v15, v1
	v_mov_b32_e32 v24, v1
	v_mov_b32_e32 v25, v1
	v_mov_b32_e32 v26, v1
	v_mov_b32_e32 v27, v1
	v_mov_b32_e32 v28, v1
	v_mov_b32_e32 v29, v1
	v_mov_b32_e32 v30, v1
	v_mov_b32_e32 v31, v1
	v_mov_b32_e32 v40, v1
	v_mov_b32_e32 v41, v1
	v_mov_b32_e32 v42, v1
	v_mov_b32_e32 v43, v1
	v_mov_b32_e32 v44, v1
	v_mov_b32_e32 v45, v1
	v_mov_b32_e32 v46, v1
	v_mov_b32_e32 v47, v1
	v_mov_b32_e32 v56, v1
	v_mov_b32_e32 v57, v1
	v_mov_b32_e32 v58, v1
	v_mov_b32_e32 v59, v1
	v_mov_b32_e32 v60, v1
	v_mov_b32_e32 v61, v1
	v_mov_b32_e32 v62, v1
	v_mov_b32_e32 v63, v1
	v_mov_b32_e32 v64, v1
	v_mov_b32_e32 v65, v1
	v_mov_b32_e32 v66, v1
	v_mov_b32_e32 v67, v1
	v_mov_b32_e32 v68, v1
	v_mov_b32_e32 v69, v1
	v_mov_b32_e32 v70, v1
	v_mov_b32_e32 v71, v1
	v_mov_b32_e32 v80, v1
	v_mov_b32_e32 v81, v1
	v_mov_b32_e32 v82, v1
	v_mov_b32_e32 v83, v1
	v_mov_b32_e32 v84, v1
	v_mov_b32_e32 v85, v1
	v_mov_b32_e32 v86, v1
	v_mov_b32_e32 v87, v1
	v_mov_b32_e32 v96, v1
	v_mov_b32_e32 v97, v1
	v_mov_b32_e32 v98, v1
	v_mov_b32_e32 v99, v1
	v_mov_b32_e32 v100, v1
	v_mov_b32_e32 v101, v1
	v_mov_b32_e32 v102, v1
	v_mov_b32_e32 v103, v1
	v_mov_b32_e32 v112, v1
	v_mov_b32_e32 v113, v1
	v_mov_b32_e32 v114, v1
	v_mov_b32_e32 v115, v1
	v_mov_b32_e32 v116, v1
	v_mov_b32_e32 v117, v1
	v_mov_b32_e32 v118, v1
	v_mov_b32_e32 v119, v1
	v_mov_b32_e32 v72, v1
	v_mov_b32_e32 v73, v1
	v_mov_b32_e32 v74, v1
	v_mov_b32_e32 v75, v1
	v_mov_b32_e32 v76, v1
	v_mov_b32_e32 v77, v1
	v_mov_b32_e32 v78, v1
	v_mov_b32_e32 v79, v1
	v_mov_b32_e32 v88, v1
	v_mov_b32_e32 v89, v1
	v_mov_b32_e32 v90, v1
	v_mov_b32_e32 v91, v1
	v_mov_b32_e32 v92, v1
	v_mov_b32_e32 v93, v1
	v_mov_b32_e32 v94, v1
	v_mov_b32_e32 v95, v1
	v_mov_b32_e32 v104, v1
	v_mov_b32_e32 v105, v1
	v_mov_b32_e32 v106, v1
	v_mov_b32_e32 v107, v1
	v_mov_b32_e32 v108, v1
	v_mov_b32_e32 v109, v1
	v_mov_b32_e32 v110, v1
	v_mov_b32_e32 v111, v1
	v_mov_b32_e32 v120, v1
	v_mov_b32_e32 v121, v1
	v_mov_b32_e32 v122, v1
	v_mov_b32_e32 v123, v1
	v_mov_b32_e32 v124, v1
	v_mov_b32_e32 v125, v1
	v_mov_b32_e32 v126, v1
	v_mov_b32_e32 v127, v1
	.p2alignl 6, 3212836864

.LBB0_461:
	s_andn2_b64 vcc, exec, s[22:23]
	s_cbranch_vccnz .LBB0_517
	s_add_u32 s2, s24, 0x100
	v_mov_b32_e32 v0, 0
	s_addc_u32 s3, s25, 0
	s_mov_b32 s12, 0
	s_waitcnt lgkmcnt(0)
	v_mov_b32_e32 v1, v0
	v_mov_b32_e32 v2, v0
	v_mov_b32_e32 v3, v0
	v_mov_b32_e32 v4, v0
	v_mov_b32_e32 v5, v0
	v_mov_b32_e32 v6, v0
	v_mov_b32_e32 v7, v0
	v_mov_b32_e32 v8, v0
	v_mov_b32_e32 v9, v0
	v_mov_b32_e32 v10, v0
	v_mov_b32_e32 v11, v0
	v_mov_b32_e32 v12, v0
	v_mov_b32_e32 v13, v0
	v_mov_b32_e32 v14, v0
	v_mov_b32_e32 v15, v0
	v_mov_b32_e32 v20, v0
	v_mov_b32_e32 v21, v0
	v_mov_b32_e32 v22, v0
	v_mov_b32_e32 v23, v0
	v_mov_b32_e32 v28, v0
	v_mov_b32_e32 v29, v0
	v_mov_b32_e32 v30, v0
	v_mov_b32_e32 v31, v0
	v_mov_b32_e32 v36, v0
	v_mov_b32_e32 v37, v0
	v_mov_b32_e32 v38, v0
	v_mov_b32_e32 v39, v0
	v_mov_b32_e32 v44, v0
	v_mov_b32_e32 v45, v0
	v_mov_b32_e32 v46, v0
	v_mov_b32_e32 v47, v0
	v_mov_b32_e32 v16, v0
	v_mov_b32_e32 v17, v0
	v_mov_b32_e32 v18, v0
	v_mov_b32_e32 v19, v0
	v_mov_b32_e32 v24, v0
	v_mov_b32_e32 v25, v0
	v_mov_b32_e32 v26, v0
	v_mov_b32_e32 v27, v0
	v_mov_b32_e32 v32, v0
	v_mov_b32_e32 v33, v0
	v_mov_b32_e32 v34, v0
	v_mov_b32_e32 v35, v0
	v_mov_b32_e32 v40, v0
	v_mov_b32_e32 v41, v0
	v_mov_b32_e32 v42, v0
	v_mov_b32_e32 v43, v0
	v_mov_b32_e32 v48, v0
	v_mov_b32_e32 v49, v0
	v_mov_b32_e32 v50, v0
	v_mov_b32_e32 v51, v0
	v_mov_b32_e32 v52, v0
	v_mov_b32_e32 v53, v0
	v_mov_b32_e32 v54, v0
	v_mov_b32_e32 v55, v0
	v_mov_b32_e32 v56, v0
	v_mov_b32_e32 v57, v0
	v_mov_b32_e32 v58, v0
	v_mov_b32_e32 v59, v0
	v_mov_b32_e32 v60, v0
	v_mov_b32_e32 v61, v0
	v_mov_b32_e32 v62, v0
	v_mov_b32_e32 v63, v0
	v_mov_b32_e32 v64, v0
	v_mov_b32_e32 v65, v0
	v_mov_b32_e32 v66, v0
	v_mov_b32_e32 v67, v0
	v_mov_b32_e32 v68, v0
	v_mov_b32_e32 v69, v0
	v_mov_b32_e32 v70, v0
	v_mov_b32_e32 v71, v0
	v_mov_b32_e32 v72, v0
	v_mov_b32_e32 v73, v0
	v_mov_b32_e32 v74, v0
	v_mov_b32_e32 v75, v0
	v_mov_b32_e32 v76, v0
	v_mov_b32_e32 v77, v0
	v_mov_b32_e32 v78, v0
	v_mov_b32_e32 v79, v0
	v_mov_b32_e32 v84, v0
	v_mov_b32_e32 v85, v0
	v_mov_b32_e32 v86, v0
	v_mov_b32_e32 v87, v0
	v_mov_b32_e32 v92, v0
	v_mov_b32_e32 v93, v0
	v_mov_b32_e32 v94, v0
	v_mov_b32_e32 v95, v0
	v_mov_b32_e32 v100, v0
	v_mov_b32_e32 v101, v0
	v_mov_b32_e32 v102, v0
	v_mov_b32_e32 v103, v0
	v_mov_b32_e32 v108, v0
	v_mov_b32_e32 v109, v0
	v_mov_b32_e32 v110, v0
	v_mov_b32_e32 v111, v0
	v_mov_b32_e32 v80, v0
	v_mov_b32_e32 v81, v0
	v_mov_b32_e32 v82, v0
	v_mov_b32_e32 v83, v0
	v_mov_b32_e32 v88, v0
	v_mov_b32_e32 v89, v0
	v_mov_b32_e32 v90, v0
	v_mov_b32_e32 v91, v0
	v_mov_b32_e32 v96, v0
	v_mov_b32_e32 v97, v0
	v_mov_b32_e32 v98, v0
	v_mov_b32_e32 v99, v0
	v_mov_b32_e32 v104, v0
	v_mov_b32_e32 v105, v0
	v_mov_b32_e32 v106, v0
	v_mov_b32_e32 v107, v0
	v_mov_b32_e32 v112, v0
	v_mov_b32_e32 v113, v0
	v_mov_b32_e32 v114, v0
	v_mov_b32_e32 v115, v0
	v_mov_b32_e32 v116, v0
	v_mov_b32_e32 v117, v0
	v_mov_b32_e32 v118, v0
	v_mov_b32_e32 v119, v0
	v_mov_b32_e32 v120, v0
	v_mov_b32_e32 v121, v0
	v_mov_b32_e32 v122, v0
	v_mov_b32_e32 v123, v0
	v_mov_b32_e32 v124, v0
	v_mov_b32_e32 v125, v0
	v_mov_b32_e32 v126, v0
	v_mov_b32_e32 v127, v0
	.p2alignl 6, 3212836864

.LBB0_648:
	s_andn2_b64 vcc, exec, s[10:11]
	s_cbranch_vccnz .LBB0_1024
	s_add_u32 s0, s0, 0x80080
	s_addc_u32 s1, s1, 0
	s_add_u32 s14, s2, 0x100
	v_mov_b32_e32 v0, 0
	s_addc_u32 s15, s3, 0
	s_mov_b32 s2, 0
	v_mov_b32_e32 v1, v0
	v_mov_b32_e32 v2, v0
	v_mov_b32_e32 v3, v0
	v_mov_b32_e32 v4, v0
	v_mov_b32_e32 v5, v0
	v_mov_b32_e32 v6, v0
	v_mov_b32_e32 v7, v0
	v_mov_b32_e32 v16, v0
	v_mov_b32_e32 v17, v0
	v_mov_b32_e32 v18, v0
	v_mov_b32_e32 v19, v0
	v_mov_b32_e32 v20, v0
	v_mov_b32_e32 v21, v0
	v_mov_b32_e32 v22, v0
	v_mov_b32_e32 v23, v0
	v_mov_b32_e32 v32, v0
	v_mov_b32_e32 v33, v0
	v_mov_b32_e32 v34, v0
	v_mov_b32_e32 v35, v0
	v_mov_b32_e32 v36, v0
	v_mov_b32_e32 v37, v0
	v_mov_b32_e32 v38, v0
	v_mov_b32_e32 v39, v0
	v_mov_b32_e32 v48, v0
	v_mov_b32_e32 v49, v0
	v_mov_b32_e32 v50, v0
	v_mov_b32_e32 v51, v0
	v_mov_b32_e32 v52, v0
	v_mov_b32_e32 v53, v0
	v_mov_b32_e32 v54, v0
	v_mov_b32_e32 v55, v0
	v_mov_b32_e32 v8, v0
	v_mov_b32_e32 v9, v0
	v_mov_b32_e32 v10, v0
	v_mov_b32_e32 v11, v0
	v_mov_b32_e32 v12, v0
	v_mov_b32_e32 v13, v0
	v_mov_b32_e32 v14, v0
	v_mov_b32_e32 v15, v0
	v_mov_b32_e32 v24, v0
	v_mov_b32_e32 v25, v0
	v_mov_b32_e32 v26, v0
	v_mov_b32_e32 v27, v0
	v_mov_b32_e32 v28, v0
	v_mov_b32_e32 v29, v0
	v_mov_b32_e32 v30, v0
	v_mov_b32_e32 v31, v0
	v_mov_b32_e32 v40, v0
	v_mov_b32_e32 v41, v0
	v_mov_b32_e32 v42, v0
	v_mov_b32_e32 v43, v0
	v_mov_b32_e32 v44, v0
	v_mov_b32_e32 v45, v0
	v_mov_b32_e32 v46, v0
	v_mov_b32_e32 v47, v0
	v_mov_b32_e32 v56, v0
	v_mov_b32_e32 v57, v0
	v_mov_b32_e32 v58, v0
	v_mov_b32_e32 v59, v0
	v_mov_b32_e32 v60, v0
	v_mov_b32_e32 v61, v0
	v_mov_b32_e32 v62, v0
	v_mov_b32_e32 v63, v0
	v_mov_b32_e32 v64, v0
	v_mov_b32_e32 v65, v0
	v_mov_b32_e32 v66, v0
	v_mov_b32_e32 v67, v0
	v_mov_b32_e32 v68, v0
	v_mov_b32_e32 v69, v0
	v_mov_b32_e32 v70, v0
	v_mov_b32_e32 v71, v0
	v_mov_b32_e32 v80, v0
	v_mov_b32_e32 v81, v0
	v_mov_b32_e32 v82, v0
	v_mov_b32_e32 v83, v0
	v_mov_b32_e32 v84, v0
	v_mov_b32_e32 v85, v0
	v_mov_b32_e32 v86, v0
	v_mov_b32_e32 v87, v0
	v_mov_b32_e32 v96, v0
	v_mov_b32_e32 v97, v0
	v_mov_b32_e32 v98, v0
	v_mov_b32_e32 v99, v0
	v_mov_b32_e32 v100, v0
	v_mov_b32_e32 v101, v0
	v_mov_b32_e32 v102, v0
	v_mov_b32_e32 v103, v0
	v_mov_b32_e32 v112, v0
	v_mov_b32_e32 v113, v0
	v_mov_b32_e32 v114, v0
	v_mov_b32_e32 v115, v0
	v_mov_b32_e32 v116, v0
	v_mov_b32_e32 v117, v0
	v_mov_b32_e32 v118, v0
	v_mov_b32_e32 v119, v0
	v_mov_b32_e32 v72, v0
	v_mov_b32_e32 v73, v0
	v_mov_b32_e32 v74, v0
	v_mov_b32_e32 v75, v0
	v_mov_b32_e32 v76, v0
	v_mov_b32_e32 v77, v0
	v_mov_b32_e32 v78, v0
	v_mov_b32_e32 v79, v0
	v_mov_b32_e32 v88, v0
	v_mov_b32_e32 v89, v0
	v_mov_b32_e32 v90, v0
	v_mov_b32_e32 v91, v0
	v_mov_b32_e32 v92, v0
	v_mov_b32_e32 v93, v0
	v_mov_b32_e32 v94, v0
	v_mov_b32_e32 v95, v0
	v_mov_b32_e32 v104, v0
	v_mov_b32_e32 v105, v0
	v_mov_b32_e32 v106, v0
	v_mov_b32_e32 v107, v0
	v_mov_b32_e32 v108, v0
	v_mov_b32_e32 v109, v0
	v_mov_b32_e32 v110, v0
	v_mov_b32_e32 v111, v0
	v_mov_b32_e32 v120, v0
	v_mov_b32_e32 v121, v0
	v_mov_b32_e32 v122, v0
	v_mov_b32_e32 v123, v0
	v_mov_b32_e32 v124, v0
	v_mov_b32_e32 v125, v0
	v_mov_b32_e32 v126, v0
	v_mov_b32_e32 v127, v0
	.p2alignl 6, 3212836864

.LBB0_1034:
	s_andn2_b64 vcc, exec, s[10:11]
	s_cbranch_vccnz .LBB0_1042
	s_add_u32 s2, s2, 0x40080
	s_addc_u32 s3, s3, 0
	s_add_u32 s14, s20, 0x100
	s_addc_u32 s15, s21, 0
	s_mov_b32 s16, 0
	v_mov_b32_e32 v0, 0
	v_mov_b32_e32 v1, 0
	v_mov_b32_e32 v2, 0
	v_mov_b32_e32 v3, 0
	v_mov_b32_e32 v4, 0
	v_mov_b32_e32 v5, 0
	v_mov_b32_e32 v6, 0
	v_mov_b32_e32 v7, 0
	v_mov_b32_e32 v16, 0
	v_mov_b32_e32 v17, 0
	v_mov_b32_e32 v18, 0
	v_mov_b32_e32 v19, 0
	v_mov_b32_e32 v20, 0
	v_mov_b32_e32 v21, 0
	v_mov_b32_e32 v22, 0
	v_mov_b32_e32 v23, 0
	v_mov_b32_e32 v32, 0
	v_mov_b32_e32 v33, 0
	v_mov_b32_e32 v34, 0
	v_mov_b32_e32 v35, 0
	v_mov_b32_e32 v36, 0
	v_mov_b32_e32 v37, 0
	v_mov_b32_e32 v38, 0
	v_mov_b32_e32 v39, 0
	v_mov_b32_e32 v48, 0
	v_mov_b32_e32 v49, 0
	v_mov_b32_e32 v50, 0
	v_mov_b32_e32 v51, 0
	v_mov_b32_e32 v52, 0
	v_mov_b32_e32 v53, 0
	v_mov_b32_e32 v54, 0
	v_mov_b32_e32 v55, 0
	v_mov_b32_e32 v8, 0
	v_mov_b32_e32 v9, 0
	v_mov_b32_e32 v10, 0
	v_mov_b32_e32 v11, 0
	v_mov_b32_e32 v12, 0
	v_mov_b32_e32 v13, 0
	v_mov_b32_e32 v14, 0
	v_mov_b32_e32 v15, 0
	v_mov_b32_e32 v24, 0
	v_mov_b32_e32 v25, 0
	v_mov_b32_e32 v26, 0
	v_mov_b32_e32 v27, 0
	v_mov_b32_e32 v28, 0
	v_mov_b32_e32 v29, 0
	v_mov_b32_e32 v30, 0
	v_mov_b32_e32 v31, 0
	v_mov_b32_e32 v40, 0
	v_mov_b32_e32 v41, 0
	v_mov_b32_e32 v42, 0
	v_mov_b32_e32 v43, 0
	v_mov_b32_e32 v44, 0
	v_mov_b32_e32 v45, 0
	v_mov_b32_e32 v46, 0
	v_mov_b32_e32 v47, 0
	v_mov_b32_e32 v56, 0
	v_mov_b32_e32 v57, 0
	v_mov_b32_e32 v58, 0
	v_mov_b32_e32 v59, 0
	v_mov_b32_e32 v60, 0
	v_mov_b32_e32 v61, 0
	v_mov_b32_e32 v62, 0
	v_mov_b32_e32 v63, 0
	v_mov_b32_e32 v64, 0
	v_mov_b32_e32 v65, 0
	v_mov_b32_e32 v66, 0
	v_mov_b32_e32 v67, 0
	v_mov_b32_e32 v68, 0
	v_mov_b32_e32 v69, 0
	v_mov_b32_e32 v70, 0
	v_mov_b32_e32 v71, 0
	v_mov_b32_e32 v84, 0
	v_mov_b32_e32 v85, 0
	v_mov_b32_e32 v86, 0
	v_mov_b32_e32 v87, 0
	v_mov_b32_e32 v96, 0
	v_mov_b32_e32 v97, 0
	v_mov_b32_e32 v98, 0
	v_mov_b32_e32 v99, 0
	v_mov_b32_e32 v112, 0
	v_mov_b32_e32 v113, 0
	v_mov_b32_e32 v114, 0
	v_mov_b32_e32 v115, 0
	v_mov_b32_e32 v116, 0
	v_mov_b32_e32 v117, 0
	v_mov_b32_e32 v118, 0
	v_mov_b32_e32 v119, 0
	v_mov_b32_e32 v128, 0
	v_mov_b32_e32 v129, 0
	v_mov_b32_e32 v130, 0
	v_mov_b32_e32 v131, 0
	v_mov_b32_e32 v92, 0
	v_mov_b32_e32 v93, 0
	v_mov_b32_e32 v94, 0
	v_mov_b32_e32 v95, 0
	v_mov_b32_e32 v72, 0
	v_mov_b32_e32 v73, 0
	v_mov_b32_e32 v74, 0
	v_mov_b32_e32 v75, 0
	v_mov_b32_e32 v80, 0
	v_mov_b32_e32 v81, 0
	v_mov_b32_e32 v82, 0
	v_mov_b32_e32 v83, 0
	v_mov_b32_e32 v104, 0
	v_mov_b32_e32 v105, 0
	v_mov_b32_e32 v106, 0
	v_mov_b32_e32 v107, 0
	v_mov_b32_e32 v108, 0
	v_mov_b32_e32 v109, 0
	v_mov_b32_e32 v110, 0
	v_mov_b32_e32 v111, 0
	v_mov_b32_e32 v120, 0
	v_mov_b32_e32 v121, 0
	v_mov_b32_e32 v122, 0
	v_mov_b32_e32 v123, 0
	v_mov_b32_e32 v124, 0
	v_mov_b32_e32 v125, 0
	v_mov_b32_e32 v126, 0
	v_mov_b32_e32 v127, 0
	v_mov_b32_e32 v132, 0
	v_mov_b32_e32 v133, 0
	v_mov_b32_e32 v134, 0
	v_mov_b32_e32 v135, 0
	v_mov_b32_e32 v136, 0
	v_mov_b32_e32 v137, 0
	v_mov_b32_e32 v138, 0
	v_mov_b32_e32 v139, 0
	.p2alignl 6, 3212836864

.LBB0_1098:
	s_xor_b64 s[30:31], s[0:1], -1
	s_and_b64 s[0:1], s[0:1], exec
	s_cselect_b32 s1, s19, s37
	v_mov_b32_e32 v174, v190
	s_lshl_b32 s14, s1, 15
	s_lshl_b32 s0, s1, 16
	s_add_u32 s4, s16, s0
	v_readfirstlane_b32 s7, v174
	s_addc_u32 s5, s17, 0
	s_ashr_i32 s0, s7, 6
	v_lshlrev_b32_e32 v1, 3, v174
	s_lshl_b32 s6, s1, 8
	s_lshl_b32 s38, s1, 2
	s_ashr_i32 s1, s0, 31
	v_ashrrev_i32_e32 v0, 4, v174
	v_and_b32_e32 v2, 0x78, v1
	v_and_b32_e32 v175, 31, v174
	v_bfe_u32 v176, v174, 5, 1
	s_lshl_b32 s39, s0, 5
	s_and_b32 s7, s7, 0x3fffffc0
	s_lshl_b64 s[28:29], s[0:1], 13
	v_lshlrev_b32_e32 v2, 1, v2
	v_lshlrev_b32_e32 v3, 8, v0
	v_lshlrev_b32_e32 v10, 8, v175
	v_lshlrev_b32_e32 v11, 4, v176
	s_add_u32 s0, s4, s28
	v_or_b32_e32 v148, v2, v3
	v_or_b32_e32 v12, v11, v10
	s_addc_u32 s1, s5, s29
	global_load_dwordx4 v[96:99], v148, s[22:23]
	global_load_dwordx4 v[100:103], v148, s[20:21]
	global_load_dwordx4 v[136:139], v148, s[42:43]
	global_load_dwordx4 v[140:143], v148, s[26:27]
	global_load_dwordx4 v[104:107], v12, s[0:1]
	global_load_dwordx4 v[108:111], v12, s[0:1] offset:32
	global_load_dwordx4 v[112:115], v12, s[0:1] offset:64
	global_load_dwordx4 v[116:119], v12, s[0:1] offset:96
	global_load_dwordx4 v[120:123], v12, s[0:1] offset:128
	global_load_dwordx4 v[124:127], v12, s[0:1] offset:160
	global_load_dwordx4 v[128:131], v12, s[0:1] offset:192
	global_load_dwordx4 v[132:135], v12, s[0:1] offset:224
	v_and_b32_e32 v6, 0xfffff0, v0
	v_lshlrev_b32_e32 v7, 1, v0
	v_and_or_b32 v6, v7, 8, v6
	v_lshrrev_b32_e32 v7, 1, v0
	v_and_b32_e32 v8, 3, v0
	v_add_u32_e32 v0, 32, v0
	v_and_b32_e32 v4, 63, v174
	v_and_b32_e32 v9, 0xfffff0, v0
	v_lshlrev_b32_e32 v0, 1, v0
	v_lshlrev_b32_e32 v12, 4, v174
	s_lshl_b32 s0, s7, 2
	v_and_or_b32 v0, v0, 8, v9
	v_lshlrev_b32_e32 v9, 3, v4
	v_and_b32_e32 v13, 0xc0, v12
	v_lshlrev_b32_e32 v14, 1, v174
	s_add_i32 s0, s0, 0
	v_lshlrev_b32_e32 v5, 2, v176
	v_and_or_b32 v13, v9, 24, v13
	v_and_b32_e32 v14, 32, v14
	v_and_b32_e32 v9, 0x100, v9
	s_add_i32 s18, s38, 4
	s_add_i32 s39, s39, s6
	s_add_i32 s4, s0, 0x10000
	v_lshrrev_b32_e32 v6, 1, v6
	v_bfe_u32 v1, v1, 5, 2
	v_lshrrev_b32_e32 v0, 1, v0
	v_or3_b32 v9, v13, v14, v9
	v_subrev_u32_e32 v13, s6, v5
	s_cmp_lg_u32 0, -1
	v_or_b32_e32 v6, v6, v1
	v_and_or_b32 v7, v7, 4, v8
	v_or_b32_e32 v0, v0, v1
	v_and_b32_e32 v1, 0x70, v174
	v_cvt_f32_i32_e32 v13, v13
	s_cselect_b32 s0, 0, 0
	v_lshlrev_b32_e32 v6, 9, v6
	v_lshlrev_b32_e32 v7, 6, v7
	v_and_b32_e32 v8, 48, v2
	v_lshlrev_b32_e32 v0, 9, v0
	v_bitop3_b32 v1, v2, v3, v1 bitop3:0xde
	v_add_u32_e32 v178, s0, v9
	s_movk_i32 s0, 0x70
	v_or3_b32 v0, v0, v7, v8
	v_or3_b32 v6, v6, v7, v8
	v_add_u32_e32 v182, 0, v1
	v_and_b32_e32 v1, 0x70, v12
	v_bitop3_b32 v2, v11, v12, s0 bitop3:0x78
	s_movk_i32 s0, 0x60
	s_waitcnt vmcnt(0)
	v_add_u32_e32 v180, 0, v6
	v_add_u32_e32 v181, 0, v0
	v_add_u32_e32 v0, 0, v10
	v_bitop3_b32 v3, v11, v1, 32 bitop3:0x36
	v_bitop3_b32 v6, v11, v1, 64 bitop3:0x36
	v_bitop3_b32 v1, v11, v1, s0 bitop3:0x36
	v_cmp_gt_u32_e64 s[0:1], 32, v4
	v_or_b32_e32 v4, s39, v175
	v_mov_b32_e32 v32, v149
	v_mov_b32_e32 v33, v149
	v_mov_b32_e32 v46, v149
	v_mov_b32_e32 v47, v149
	v_mul_f32_e32 v179, v172, v13
	v_add_u32_e32 v177, s4, v11
	v_sub_u32_e32 v184, v4, v5
	v_mov_b32_e32 v34, v149
	v_mov_b32_e32 v35, v149
	v_mov_b32_e32 v36, v149
	v_mov_b32_e32 v37, v149
	v_mov_b32_e32 v38, v149
	v_mov_b32_e32 v39, v149
	v_mov_b32_e32 v40, v149
	v_mov_b32_e32 v41, v149
	v_mov_b32_e32 v42, v149
	v_mov_b32_e32 v43, v149
	v_mov_b32_e32 v44, v149
	v_mov_b32_e32 v45, v149
	v_add_u32_e32 v186, v0, v2
	v_add_u32_e32 v187, v0, v3
	v_add_u32_e32 v188, v0, v6
	v_add_u32_e32 v189, v0, v1
	v_mov_b64_e32 v[62:63], v[46:47]
	v_mov_b64_e32 v[16:17], v[32:33]
	v_mov_b64_e32 v[0:1], v[32:33]
	s_mov_b32 s12, 0
	v_lshl_add_u32 v183, v175, 2, s4
	v_mov_b32_e32 v203, 0xf149f2ca
	v_mov_b32_e32 v185, 0
	s_movk_i32 s13, 0x7f
	s_mov_b64 s[46:47], s[2:3]
	s_mov_b64 s[40:41], s[24:25]
	v_mov_b64_e32 v[60:61], v[44:45]
	v_mov_b64_e32 v[58:59], v[42:43]
	v_mov_b64_e32 v[56:57], v[40:41]
	v_mov_b64_e32 v[54:55], v[38:39]
	v_mov_b64_e32 v[52:53], v[36:37]
	v_mov_b64_e32 v[50:51], v[34:35]
	v_mov_b64_e32 v[48:49], v[32:33]
	v_mov_b64_e32 v[18:19], v[34:35]
	v_mov_b64_e32 v[20:21], v[36:37]
	v_mov_b64_e32 v[22:23], v[38:39]
	v_mov_b64_e32 v[24:25], v[40:41]
	v_mov_b64_e32 v[26:27], v[42:43]
	v_mov_b64_e32 v[28:29], v[44:45]
	v_mov_b64_e32 v[30:31], v[46:47]
	v_mov_b64_e32 v[2:3], v[34:35]
	v_mov_b64_e32 v[4:5], v[36:37]
	v_mov_b64_e32 v[6:7], v[38:39]
	v_mov_b64_e32 v[8:9], v[40:41]
	v_mov_b64_e32 v[10:11], v[42:43]
	v_mov_b64_e32 v[12:13], v[44:45]
	v_mov_b64_e32 v[14:15], v[46:47]
	s_waitcnt vmcnt(11)
	ds_write_b128 v180, v[96:99]
	s_waitcnt vmcnt(10)
	ds_write_b128 v181, v[100:103]
	s_waitcnt vmcnt(9)
	ds_write_b128 v182, v[136:139] offset:32768
	s_waitcnt vmcnt(8)
	ds_write_b128 v182, v[140:143] offset:40960
	s_waitcnt lgkmcnt(0)
	s_barrier
	v_add_u32_e32 v168, 0x4000, v148
	global_load_dwordx4 v[136:139], v168, s[42:43]
	global_load_dwordx4 v[140:143], v168, s[26:27]
	v_add_u32_e32 v169, 0x4000, v168
	s_mov_b32 s13, 0
	s_mov_b32 s12, 0
	s_mov_b32 s10, 0x3e0293ee
	s_mov_b32 s6, 0x11000
	s_mov_b32 s7, 0
	s_mov_b32 s8, 0x4000
	ds_read_b128 v[236:239], v186 offset:32768
	ds_read_b128 v[240:243], v186 offset:40960
	v_mov_b32_e32 v244, 0
	v_mov_b32_e32 v245, 0
	v_mov_b32_e32 v246, 0
	v_mov_b32_e32 v247, 0
	v_add_u32_e32 v200, s6, v180
	v_add_u32_e32 v201, s6, v181
	ds_write_b128 v200, v[244:247]
	ds_write_b128 v201, v[244:247]
	v_mov_b32_e32 v204, 0
	v_mov_b32_e32 v205, 0
	v_mov_b32_e32 v206, 0
	v_mov_b32_e32 v207, 0
	v_mov_b32_e32 v208, 0
	v_mov_b32_e32 v209, 0
	v_mov_b32_e32 v210, 0
	v_mov_b32_e32 v211, 0
	v_mov_b32_e32 v212, 0
	v_mov_b32_e32 v213, 0
	v_mov_b32_e32 v214, 0
	v_mov_b32_e32 v215, 0
	v_mov_b32_e32 v216, 0
	v_mov_b32_e32 v217, 0
	v_mov_b32_e32 v218, 0
	v_mov_b32_e32 v219, 0
	v_cvt_f32_u32_e32 v64, s13
	v_mov_b32_e32 v165, v164
	v_fma_f32 v64, v172, v64, v179
	v_add_f32_e32 v68, v173, v64
	v_add_f32_e32 v72, v173, v68
	v_add_f32_e32 v76, v173, v72
	v_add_f32_e32 v65, v172, v64
	v_add_f32_e32 v69, v172, v68
	v_add_f32_e32 v73, v172, v72
	v_add_f32_e32 v77, v172, v76
	v_pk_add_f32 v[66:67], v[162:163], v[64:65] op_sel_hi:[1,0]
	v_pk_add_f32 v[70:71], v[162:163], v[68:69] op_sel_hi:[1,0]
	v_pk_add_f32 v[74:75], v[162:163], v[72:73] op_sel_hi:[1,0]
	v_pk_add_f32 v[78:79], v[162:163], v[76:77] op_sel_hi:[1,0]
	v_pk_add_f32 v[82:83], v[164:165], v[66:67]
	v_pk_add_f32 v[80:81], v[166:167], v[64:65]
	v_pk_add_f32 v[86:87], v[164:165], v[70:71]
	v_pk_add_f32 v[84:85], v[164:165], v[68:69]
	v_pk_add_f32 v[90:91], v[164:165], v[74:75]
	v_pk_add_f32 v[88:89], v[164:165], v[72:73]
	v_pk_add_f32 v[94:95], v[164:165], v[78:79]
	v_pk_add_f32 v[92:93], v[164:165], v[76:77]
	s_addk_i32 s13, 0x40
	s_waitcnt lgkmcnt(3)
	v_mfma_f32_32x32x16_bf16 v[64:79], v[236:239], v[104:107], v[64:79]
	ds_read_b128 v[236:239], v187 offset:32768
	s_waitcnt lgkmcnt(3)
	v_mfma_f32_32x32x16_bf16 v[80:95], v[240:243], v[104:107], v[80:95]
	ds_read_b128 v[240:243], v187 offset:40960
	s_waitcnt lgkmcnt(1)
	v_mfma_f32_32x32x16_bf16 v[64:79], v[236:239], v[108:111], v[64:79]
	ds_read_b128 v[236:239], v188 offset:32768
	s_waitcnt lgkmcnt(1)
	v_mfma_f32_32x32x16_bf16 v[80:95], v[240:243], v[108:111], v[80:95]
	ds_read_b128 v[240:243], v188 offset:40960
	s_waitcnt lgkmcnt(1)
	v_mfma_f32_32x32x16_bf16 v[64:79], v[236:239], v[112:115], v[64:79]
	ds_read_b128 v[236:239], v189 offset:32768
	s_waitcnt lgkmcnt(1)
	v_mfma_f32_32x32x16_bf16 v[80:95], v[240:243], v[112:115], v[80:95]
	ds_read_b128 v[240:243], v189 offset:40960
	s_waitcnt lgkmcnt(1)
	v_mfma_f32_32x32x16_bf16 v[64:79], v[236:239], v[116:119], v[64:79]
	ds_read_b128 v[236:239], v186 offset:32896
	s_waitcnt lgkmcnt(1)
	v_mfma_f32_32x32x16_bf16 v[80:95], v[240:243], v[116:119], v[80:95]
	ds_read_b128 v[240:243], v186 offset:41088
	s_waitcnt lgkmcnt(1)
	v_mfma_f32_32x32x16_bf16 v[64:79], v[236:239], v[120:123], v[64:79]
	ds_read_b128 v[236:239], v187 offset:32896
	s_waitcnt lgkmcnt(1)
	v_mfma_f32_32x32x16_bf16 v[80:95], v[240:243], v[120:123], v[80:95]
	ds_read_b128 v[240:243], v187 offset:41088
	s_waitcnt lgkmcnt(1)
	v_mfma_f32_32x32x16_bf16 v[64:79], v[236:239], v[124:127], v[64:79]
	ds_read_b128 v[236:239], v188 offset:32896
	s_waitcnt lgkmcnt(1)
	v_mfma_f32_32x32x16_bf16 v[80:95], v[240:243], v[124:127], v[80:95]
	ds_read_b128 v[240:243], v188 offset:41088
	s_waitcnt lgkmcnt(1)
	v_mfma_f32_32x32x16_bf16 v[64:79], v[236:239], v[128:131], v[64:79]
	ds_read_b128 v[236:239], v189 offset:32896
	s_waitcnt lgkmcnt(1)
	v_mfma_f32_32x32x16_bf16 v[80:95], v[240:243], v[128:131], v[80:95]
	ds_read_b128 v[240:243], v189 offset:41088
	s_waitcnt lgkmcnt(1)
	v_mfma_f32_32x32x16_bf16 v[64:79], v[236:239], v[132:135], v[64:79]
	s_waitcnt lgkmcnt(0)
	v_mfma_f32_32x32x16_bf16 v[80:95], v[240:243], v[132:135], v[80:95]
	s_waitcnt vmcnt(0)
	ds_write_b128 v182, v[136:139] offset:49152
	ds_write_b128 v182, v[140:143] offset:57344
	s_waitcnt lgkmcnt(0)
	s_barrier
	.p2alignl 6, 3212836864

.LBB0_1253:
	v_lshl_add_u64 v[8:9], s[4:5], 0, v[148:149]
	v_mov_b32_e32 v133, v149
	v_lshl_add_u64 v[10:11], s[4:5], 0, v[132:133]
	v_mov_b32_e32 v137, v149
	s_add_i32 m0, s17, 0x18000
	v_lshl_add_u64 v[8:9], v[8:9], 0, s[84:85]
	v_lshl_add_u64 v[12:13], s[0:1], 0, v[136:137]
	v_mov_b32_e32 v135, v149
	s_and_b32 s14, s8, 3
	s_waitcnt vmcnt(2)
	s_barrier
	global_load_lds_dwordx4 v[8:9], off
	v_lshl_add_u64 v[8:9], v[10:11], 0, s[84:85]
	s_add_i32 m0, s17, 0x1a000
	s_add_i32 s26, s17, 0x8000
	s_add_i32 s27, s17, 0xa000
	v_lshl_add_u64 v[14:15], s[0:1], 0, v[134:135]
	global_load_lds_dwordx4 v[8:9], off
	v_lshl_add_u64 v[8:9], v[12:13], 0, s[84:85]
	s_mov_b32 m0, s26
	s_add_u32 s8, s4, 0x10080
	global_load_lds_dwordx4 v[8:9], off
	v_lshl_add_u64 v[8:9], v[14:15], 0, s[84:85]
	s_mov_b32 m0, s27
	s_addc_u32 s9, s5, 0
	global_load_lds_dwordx4 v[8:9], off
	s_add_i32 m0, s17, 0x1c000
	v_lshl_add_u64 v[8:9], s[8:9], 0, v[148:149]
	global_load_lds_dwordx4 v[8:9], off
	v_lshl_add_u64 v[8:9], s[8:9], 0, v[132:133]
	s_add_i32 m0, s17, 0x1e000
	v_and_b32_e32 v131, 15, v3
	global_load_lds_dwordx4 v[8:9], off
	s_waitcnt vmcnt(6)
	v_bfe_u32 v142, v3, 4, 2
	v_lshl_or_b32 v130, s13, 6, v131
	v_lshlrev_b32_e32 v129, 2, v131
	s_cmp_lt_i32 s15, 1
	v_lshlrev_b32_e32 v128, 4, v142
	s_barrier
	s_cbranch_scc1 .LBB0_1256
	v_lshlrev_b32_e32 v3, 6, v130
	s_movk_i32 s9, 0x3c0
	v_lshlrev_b32_e32 v7, 2, v130
	v_and_or_b32 v3, v3, s9, v128
	s_lshl_b32 s9, s13, 13
	v_and_b32_e32 v7, 32, v7
	s_and_b32 s8, s23, 3
	v_bitop3_b32 v3, v3, s9, v7 bitop3:0xde
	v_lshl_or_b32 v7, v131, 6, v128
	s_lshl_b32 s9, s14, 12
	v_and_b32_e32 v8, 32, v129
	s_add_i32 s28, s15, -2
	s_lshl_b32 s8, s8, 9
	v_bitop3_b32 v143, v7, s9, v8 bitop3:0xde
	v_lshlrev_b32_e32 v7, 14, v5
	s_add_u32 s6, s6, s8
	v_and_b32_e32 v7, 0xffff8000, v7
	s_addc_u32 s7, s7, 0
	v_lshl_add_u32 v4, v4, 11, v7
	v_and_b32_e32 v5, 1, v5
	v_readlane_b32 s8, v254, 41
	v_lshl_or_b32 v4, v5, 6, v4
	s_add_u32 s6, s8, s6
	v_readlane_b32 s8, v254, 42
	v_lshl_add_u32 v4, v6, 1, v4
	v_mov_b32_e32 v5, v149
	s_addc_u32 s7, s8, s7
	v_lshl_add_u64 v[138:139], s[6:7], 0, v[4:5]
	v_lshlrev_b32_e32 v4, 14, v0
	v_and_b32_e32 v4, 0xffff8000, v4
	v_lshl_add_u32 v1, v1, 11, v4
	v_and_b32_e32 v0, 1, v0
	v_lshl_or_b32 v0, v0, 6, v1
	v_lshl_add_u32 v0, v2, 1, v0
	v_mov_b32_e32 v1, v149
	v_lshl_add_u64 v[140:141], s[6:7], 0, v[0:1]
	v_mov_b32_e32 v0, 0
	s_mov_b32 s10, 0
	s_mov_b64 s[6:7], 0
	v_add_u32_e32 v162, 0, v3
	v_mov_b32_e32 v1, v0
	v_mov_b32_e32 v2, v0
	v_mov_b32_e32 v3, v0
	v_mov_b32_e32 v4, v0
	v_mov_b32_e32 v5, v0
	v_mov_b32_e32 v6, v0
	v_mov_b32_e32 v7, v0
	v_mov_b32_e32 v16, v0
	v_mov_b32_e32 v17, v0
	v_mov_b32_e32 v18, v0
	v_mov_b32_e32 v19, v0
	v_mov_b32_e32 v20, v0
	v_mov_b32_e32 v21, v0
	v_mov_b32_e32 v22, v0
	v_mov_b32_e32 v23, v0
	v_mov_b32_e32 v32, v0
	v_mov_b32_e32 v33, v0
	v_mov_b32_e32 v34, v0
	v_mov_b32_e32 v35, v0
	v_mov_b32_e32 v36, v0
	v_mov_b32_e32 v37, v0
	v_mov_b32_e32 v38, v0
	v_mov_b32_e32 v39, v0
	v_mov_b32_e32 v48, v0
	v_mov_b32_e32 v49, v0
	v_mov_b32_e32 v50, v0
	v_mov_b32_e32 v51, v0
	v_mov_b32_e32 v52, v0
	v_mov_b32_e32 v53, v0
	v_mov_b32_e32 v54, v0
	v_mov_b32_e32 v55, v0
	v_mov_b32_e32 v8, v0
	v_mov_b32_e32 v9, v0
	v_mov_b32_e32 v10, v0
	v_mov_b32_e32 v11, v0
	v_mov_b32_e32 v12, v0
	v_mov_b32_e32 v13, v0
	v_mov_b32_e32 v14, v0
	v_mov_b32_e32 v15, v0
	v_mov_b32_e32 v24, v0
	v_mov_b32_e32 v25, v0
	v_mov_b32_e32 v26, v0
	v_mov_b32_e32 v27, v0
	v_mov_b32_e32 v28, v0
	v_mov_b32_e32 v29, v0
	v_mov_b32_e32 v30, v0
	v_mov_b32_e32 v31, v0
	v_mov_b32_e32 v40, v0
	v_mov_b32_e32 v41, v0
	v_mov_b32_e32 v42, v0
	v_mov_b32_e32 v43, v0
	v_mov_b32_e32 v44, v0
	v_mov_b32_e32 v45, v0
	v_mov_b32_e32 v46, v0
	v_mov_b32_e32 v47, v0
	v_mov_b32_e32 v56, v0
	v_mov_b32_e32 v57, v0
	v_mov_b32_e32 v58, v0
	v_mov_b32_e32 v59, v0
	v_mov_b32_e32 v60, v0
	v_mov_b32_e32 v61, v0
	v_mov_b32_e32 v62, v0
	v_mov_b32_e32 v63, v0
	v_mov_b32_e32 v64, v0
	v_mov_b32_e32 v65, v0
	v_mov_b32_e32 v66, v0
	v_mov_b32_e32 v67, v0
	v_mov_b32_e32 v68, v0
	v_mov_b32_e32 v69, v0
	v_mov_b32_e32 v70, v0
	v_mov_b32_e32 v71, v0
	v_mov_b32_e32 v80, v0
	v_mov_b32_e32 v81, v0
	v_mov_b32_e32 v82, v0
	v_mov_b32_e32 v83, v0
	v_mov_b32_e32 v84, v0
	v_mov_b32_e32 v85, v0
	v_mov_b32_e32 v86, v0
	v_mov_b32_e32 v87, v0
	v_mov_b32_e32 v96, v0
	v_mov_b32_e32 v97, v0
	v_mov_b32_e32 v98, v0
	v_mov_b32_e32 v99, v0
	v_mov_b32_e32 v100, v0
	v_mov_b32_e32 v101, v0
	v_mov_b32_e32 v102, v0
	v_mov_b32_e32 v103, v0
	v_mov_b32_e32 v112, v0
	v_mov_b32_e32 v113, v0
	v_mov_b32_e32 v114, v0
	v_mov_b32_e32 v115, v0
	v_mov_b32_e32 v116, v0
	v_mov_b32_e32 v117, v0
	v_mov_b32_e32 v118, v0
	v_mov_b32_e32 v119, v0
	v_mov_b32_e32 v72, v0
	v_mov_b32_e32 v73, v0
	v_mov_b32_e32 v74, v0
	v_mov_b32_e32 v75, v0
	v_mov_b32_e32 v76, v0
	v_mov_b32_e32 v77, v0
	v_mov_b32_e32 v78, v0
	v_mov_b32_e32 v79, v0
	v_mov_b32_e32 v88, v0
	v_mov_b32_e32 v89, v0
	v_mov_b32_e32 v90, v0
	v_mov_b32_e32 v91, v0
	v_mov_b32_e32 v92, v0
	v_mov_b32_e32 v93, v0
	v_mov_b32_e32 v94, v0
	v_mov_b32_e32 v95, v0
	v_mov_b32_e32 v104, v0
	v_mov_b32_e32 v105, v0
	v_mov_b32_e32 v106, v0
	v_mov_b32_e32 v107, v0
	v_mov_b32_e32 v108, v0
	v_mov_b32_e32 v109, v0
	v_mov_b32_e32 v110, v0
	v_mov_b32_e32 v111, v0
	v_mov_b32_e32 v120, v0
	v_mov_b32_e32 v121, v0
	v_mov_b32_e32 v122, v0
	v_mov_b32_e32 v123, v0
	v_mov_b32_e32 v124, v0
	v_mov_b32_e32 v125, v0
	v_mov_b32_e32 v126, v0
	v_mov_b32_e32 v127, v0
	.p2alignl 6, 3212836864

.LBB0_1293:
	v_lshl_add_u64 v[8:9], s[2:3], 0, v[148:149]
	v_mov_b32_e32 v133, v149
	v_lshl_add_u64 v[10:11], s[2:3], 0, v[132:133]
	v_mov_b32_e32 v137, v149
	s_lshl_b32 s5, s5, 5
	s_add_i32 m0, s14, 0x18000
	v_lshl_add_u64 v[8:9], v[8:9], 0, s[84:85]
	v_lshl_add_u64 v[12:13], s[34:35], 0, v[136:137]
	v_mov_b32_e32 v135, v149
	s_and_b32 s11, s5, 0x60
	s_waitcnt vmcnt(2)
	s_barrier
	global_load_lds_dwordx4 v[8:9], off
	v_lshl_add_u64 v[8:9], v[10:11], 0, s[84:85]
	s_add_i32 m0, s14, 0x1a000
	s_add_i32 s18, s14, 0x8000
	s_add_i32 s19, s14, 0xa000
	v_lshl_add_u64 v[14:15], s[34:35], 0, v[134:135]
	global_load_lds_dwordx4 v[8:9], off
	v_lshl_add_u64 v[8:9], v[12:13], 0, s[84:85]
	s_mov_b32 m0, s18
	s_add_u32 s6, s2, 0x10080
	global_load_lds_dwordx4 v[8:9], off
	v_lshl_add_u64 v[8:9], v[14:15], 0, s[84:85]
	s_mov_b32 m0, s19
	s_addc_u32 s7, s3, 0
	global_load_lds_dwordx4 v[8:9], off
	s_add_i32 m0, s14, 0x1c000
	v_lshl_add_u64 v[8:9], s[6:7], 0, v[148:149]
	global_load_lds_dwordx4 v[8:9], off
	v_lshl_add_u64 v[8:9], s[6:7], 0, v[132:133]
	s_add_i32 m0, s14, 0x1e000
	v_and_b32_e32 v7, 15, v3
	global_load_lds_dwordx4 v[8:9], off
	v_lshrrev_b32_e32 v3, 1, v3
	s_waitcnt vmcnt(6)
	v_and_b32_e32 v3, 24, v3
	v_lshl_or_b32 v130, s4, 6, v7
	s_cmp_lt_i32 s12, 1
	v_lshlrev_b32_e32 v128, 1, v3
	s_barrier
	s_cbranch_scc1 .LBB0_1296
	v_lshlrev_b32_e32 v3, 6, v130
	s_movk_i32 s5, 0x3c0
	v_lshlrev_b32_e32 v8, 2, v130
	v_and_or_b32 v3, v3, s5, v128
	s_lshl_b32 s4, s4, 13
	v_and_b32_e32 v8, 32, v8
	v_bitop3_b32 v3, v3, s4, v8 bitop3:0xde
	v_lshl_or_b32 v8, v7, 6, v128
	v_lshlrev_b32_e32 v7, 2, v7
	s_lshl_b32 s4, s11, 7
	v_and_b32_e32 v7, 32, v7
	v_bitop3_b32 v129, v8, s4, v7 bitop3:0xde
	v_lshlrev_b32_e32 v7, 12, v5
	v_and_b32_e32 v7, 0xffffe000, v7
	v_lshl_add_u32 v4, v4, 9, v7
	v_and_b32_e32 v5, 1, v5
	v_lshl_or_b32 v4, v5, 6, v4
	v_readlane_b32 s4, v254, 43
	v_lshl_add_u32 v4, v6, 1, v4
	v_mov_b32_e32 v5, v149
	v_readlane_b32 s5, v254, 44
	s_add_i32 s20, s12, -2
	s_mov_b32 s6, 0
	v_lshl_add_u64 v[138:139], s[4:5], 0, v[4:5]
	v_lshlrev_b32_e32 v4, 12, v0
	v_and_b32_e32 v4, 0xffffe000, v4
	v_lshl_add_u32 v1, v1, 9, v4
	v_and_b32_e32 v0, 1, v0
	v_lshl_or_b32 v0, v0, 6, v1
	v_lshl_add_u32 v0, v2, 1, v0
	v_mov_b32_e32 v1, v149
	v_lshl_add_u64 v[140:141], s[4:5], 0, v[0:1]
	v_mov_b32_e32 v0, 0
	s_mov_b64 s[4:5], 0x1010080
	v_add_u32_e32 v131, 0, v3
	v_mov_b32_e32 v1, v0
	v_mov_b32_e32 v2, v0
	v_mov_b32_e32 v3, v0
	v_mov_b32_e32 v4, v0
	v_mov_b32_e32 v5, v0
	v_mov_b32_e32 v6, v0
	v_mov_b32_e32 v7, v0
	v_mov_b32_e32 v16, v0
	v_mov_b32_e32 v17, v0
	v_mov_b32_e32 v18, v0
	v_mov_b32_e32 v19, v0
	v_mov_b32_e32 v20, v0
	v_mov_b32_e32 v21, v0
	v_mov_b32_e32 v22, v0
	v_mov_b32_e32 v23, v0
	v_mov_b32_e32 v32, v0
	v_mov_b32_e32 v33, v0
	v_mov_b32_e32 v34, v0
	v_mov_b32_e32 v35, v0
	v_mov_b32_e32 v36, v0
	v_mov_b32_e32 v37, v0
	v_mov_b32_e32 v38, v0
	v_mov_b32_e32 v39, v0
	v_mov_b32_e32 v48, v0
	v_mov_b32_e32 v49, v0
	v_mov_b32_e32 v50, v0
	v_mov_b32_e32 v51, v0
	v_mov_b32_e32 v52, v0
	v_mov_b32_e32 v53, v0
	v_mov_b32_e32 v54, v0
	v_mov_b32_e32 v55, v0
	v_mov_b32_e32 v8, v0
	v_mov_b32_e32 v9, v0
	v_mov_b32_e32 v10, v0
	v_mov_b32_e32 v11, v0
	v_mov_b32_e32 v12, v0
	v_mov_b32_e32 v13, v0
	v_mov_b32_e32 v14, v0
	v_mov_b32_e32 v15, v0
	v_mov_b32_e32 v24, v0
	v_mov_b32_e32 v25, v0
	v_mov_b32_e32 v26, v0
	v_mov_b32_e32 v27, v0
	v_mov_b32_e32 v28, v0
	v_mov_b32_e32 v29, v0
	v_mov_b32_e32 v30, v0
	v_mov_b32_e32 v31, v0
	v_mov_b32_e32 v40, v0
	v_mov_b32_e32 v41, v0
	v_mov_b32_e32 v42, v0
	v_mov_b32_e32 v43, v0
	v_mov_b32_e32 v44, v0
	v_mov_b32_e32 v45, v0
	v_mov_b32_e32 v46, v0
	v_mov_b32_e32 v47, v0
	v_mov_b32_e32 v56, v0
	v_mov_b32_e32 v57, v0
	v_mov_b32_e32 v58, v0
	v_mov_b32_e32 v59, v0
	v_mov_b32_e32 v60, v0
	v_mov_b32_e32 v61, v0
	v_mov_b32_e32 v62, v0
	v_mov_b32_e32 v63, v0
	v_mov_b32_e32 v64, v0
	v_mov_b32_e32 v65, v0
	v_mov_b32_e32 v66, v0
	v_mov_b32_e32 v67, v0
	v_mov_b32_e32 v68, v0
	v_mov_b32_e32 v69, v0
	v_mov_b32_e32 v70, v0
	v_mov_b32_e32 v71, v0
	v_mov_b32_e32 v80, v0
	v_mov_b32_e32 v81, v0
	v_mov_b32_e32 v82, v0
	v_mov_b32_e32 v83, v0
	v_mov_b32_e32 v84, v0
	v_mov_b32_e32 v85, v0
	v_mov_b32_e32 v86, v0
	v_mov_b32_e32 v87, v0
	v_mov_b32_e32 v96, v0
	v_mov_b32_e32 v97, v0
	v_mov_b32_e32 v98, v0
	v_mov_b32_e32 v99, v0
	v_mov_b32_e32 v100, v0
	v_mov_b32_e32 v101, v0
	v_mov_b32_e32 v102, v0
	v_mov_b32_e32 v103, v0
	v_mov_b32_e32 v112, v0
	v_mov_b32_e32 v113, v0
	v_mov_b32_e32 v114, v0
	v_mov_b32_e32 v115, v0
	v_mov_b32_e32 v116, v0
	v_mov_b32_e32 v117, v0
	v_mov_b32_e32 v118, v0
	v_mov_b32_e32 v119, v0
	v_mov_b32_e32 v72, v0
	v_mov_b32_e32 v73, v0
	v_mov_b32_e32 v74, v0
	v_mov_b32_e32 v75, v0
	v_mov_b32_e32 v76, v0
	v_mov_b32_e32 v77, v0
	v_mov_b32_e32 v78, v0
	v_mov_b32_e32 v79, v0
	v_mov_b32_e32 v88, v0
	v_mov_b32_e32 v89, v0
	v_mov_b32_e32 v90, v0
	v_mov_b32_e32 v91, v0
	v_mov_b32_e32 v92, v0
	v_mov_b32_e32 v93, v0
	v_mov_b32_e32 v94, v0
	v_mov_b32_e32 v95, v0
	v_mov_b32_e32 v104, v0
	v_mov_b32_e32 v105, v0
	v_mov_b32_e32 v106, v0
	v_mov_b32_e32 v107, v0
	v_mov_b32_e32 v108, v0
	v_mov_b32_e32 v109, v0
	v_mov_b32_e32 v110, v0
	v_mov_b32_e32 v111, v0
	v_mov_b32_e32 v120, v0
	v_mov_b32_e32 v121, v0
	v_mov_b32_e32 v122, v0
	v_mov_b32_e32 v123, v0
	v_mov_b32_e32 v124, v0
	v_mov_b32_e32 v125, v0
	v_mov_b32_e32 v126, v0
	v_mov_b32_e32 v127, v0
	.p2alignl 6, 3212836864

.LBB0_1624:
	s_andn2_b64 vcc, exec, s[6:7]
	s_cbranch_vccnz .LBB0_1730
	s_add_u32 s2, s2, 0x40080
	s_addc_u32 s3, s3, 0
	s_add_u32 s11, s20, 0x100
	v_mov_b32_e32 v0, 0
	s_addc_u32 s15, s21, 0
	s_mov_b32 s16, 0
	v_mov_b32_e32 v1, v0
	v_mov_b32_e32 v2, v0
	v_mov_b32_e32 v3, v0
	v_mov_b32_e32 v4, v0
	v_mov_b32_e32 v5, v0
	v_mov_b32_e32 v6, v0
	v_mov_b32_e32 v7, v0
	v_mov_b32_e32 v16, v0
	v_mov_b32_e32 v17, v0
	v_mov_b32_e32 v18, v0
	v_mov_b32_e32 v19, v0
	v_mov_b32_e32 v20, v0
	v_mov_b32_e32 v21, v0
	v_mov_b32_e32 v22, v0
	v_mov_b32_e32 v23, v0
	v_mov_b32_e32 v32, v0
	v_mov_b32_e32 v33, v0
	v_mov_b32_e32 v34, v0
	v_mov_b32_e32 v35, v0
	v_mov_b32_e32 v36, v0
	v_mov_b32_e32 v37, v0
	v_mov_b32_e32 v38, v0
	v_mov_b32_e32 v39, v0
	v_mov_b32_e32 v48, v0
	v_mov_b32_e32 v49, v0
	v_mov_b32_e32 v50, v0
	v_mov_b32_e32 v51, v0
	v_mov_b32_e32 v52, v0
	v_mov_b32_e32 v53, v0
	v_mov_b32_e32 v54, v0
	v_mov_b32_e32 v55, v0
	v_mov_b32_e32 v8, v0
	v_mov_b32_e32 v9, v0
	v_mov_b32_e32 v10, v0
	v_mov_b32_e32 v11, v0
	v_mov_b32_e32 v12, v0
	v_mov_b32_e32 v13, v0
	v_mov_b32_e32 v14, v0
	v_mov_b32_e32 v15, v0
	v_mov_b32_e32 v24, v0
	v_mov_b32_e32 v25, v0
	v_mov_b32_e32 v26, v0
	v_mov_b32_e32 v27, v0
	v_mov_b32_e32 v28, v0
	v_mov_b32_e32 v29, v0
	v_mov_b32_e32 v30, v0
	v_mov_b32_e32 v31, v0
	v_mov_b32_e32 v40, v0
	v_mov_b32_e32 v41, v0
	v_mov_b32_e32 v42, v0
	v_mov_b32_e32 v43, v0
	v_mov_b32_e32 v44, v0
	v_mov_b32_e32 v45, v0
	v_mov_b32_e32 v46, v0
	v_mov_b32_e32 v47, v0
	v_mov_b32_e32 v56, v0
	v_mov_b32_e32 v57, v0
	v_mov_b32_e32 v58, v0
	v_mov_b32_e32 v59, v0
	v_mov_b32_e32 v60, v0
	v_mov_b32_e32 v61, v0
	v_mov_b32_e32 v62, v0
	v_mov_b32_e32 v63, v0
	v_mov_b32_e32 v64, v0
	v_mov_b32_e32 v65, v0
	v_mov_b32_e32 v66, v0
	v_mov_b32_e32 v67, v0
	v_mov_b32_e32 v68, v0
	v_mov_b32_e32 v69, v0
	v_mov_b32_e32 v70, v0
	v_mov_b32_e32 v71, v0
	v_mov_b32_e32 v80, v0
	v_mov_b32_e32 v81, v0
	v_mov_b32_e32 v82, v0
	v_mov_b32_e32 v83, v0
	v_mov_b32_e32 v84, v0
	v_mov_b32_e32 v85, v0
	v_mov_b32_e32 v86, v0
	v_mov_b32_e32 v87, v0
	v_mov_b32_e32 v96, v0
	v_mov_b32_e32 v97, v0
	v_mov_b32_e32 v98, v0
	v_mov_b32_e32 v99, v0
	v_mov_b32_e32 v100, v0
	v_mov_b32_e32 v101, v0
	v_mov_b32_e32 v102, v0
	v_mov_b32_e32 v103, v0
	v_mov_b32_e32 v112, v0
	v_mov_b32_e32 v113, v0
	v_mov_b32_e32 v114, v0
	v_mov_b32_e32 v115, v0
	v_mov_b32_e32 v116, v0
	v_mov_b32_e32 v117, v0
	v_mov_b32_e32 v118, v0
	v_mov_b32_e32 v119, v0
	v_mov_b32_e32 v72, v0
	v_mov_b32_e32 v73, v0
	v_mov_b32_e32 v74, v0
	v_mov_b32_e32 v75, v0
	v_mov_b32_e32 v76, v0
	v_mov_b32_e32 v77, v0
	v_mov_b32_e32 v78, v0
	v_mov_b32_e32 v79, v0
	v_mov_b32_e32 v88, v0
	v_mov_b32_e32 v89, v0
	v_mov_b32_e32 v90, v0
	v_mov_b32_e32 v91, v0
	v_mov_b32_e32 v92, v0
	v_mov_b32_e32 v93, v0
	v_mov_b32_e32 v94, v0
	v_mov_b32_e32 v95, v0
	v_mov_b32_e32 v104, v0
	v_mov_b32_e32 v105, v0
	v_mov_b32_e32 v106, v0
	v_mov_b32_e32 v107, v0
	v_mov_b32_e32 v108, v0
	v_mov_b32_e32 v109, v0
	v_mov_b32_e32 v110, v0
	v_mov_b32_e32 v111, v0
	v_mov_b32_e32 v120, v0
	v_mov_b32_e32 v121, v0
	v_mov_b32_e32 v122, v0
	v_mov_b32_e32 v123, v0
	v_mov_b32_e32 v124, v0
	v_mov_b32_e32 v125, v0
	v_mov_b32_e32 v126, v0
	v_mov_b32_e32 v127, v0
	.p2alignl 6, 3212836864

.LBB0_1798:
	s_andn2_b64 vcc, exec, s[10:11]
	s_cbranch_vccnz .LBB0_1854
	s_add_u32 s26, s26, 0x80080
	s_addc_u32 s27, s27, 0
	s_add_u32 s23, s30, 0x100
	v_mov_b32_e32 v0, 0
	s_addc_u32 s25, s31, 0
	s_mov_b32 s29, 0
	s_waitcnt lgkmcnt(0)
	v_mov_b32_e32 v1, v0
	v_mov_b32_e32 v2, v0
	v_mov_b32_e32 v3, v0
	v_mov_b32_e32 v4, v0
	v_mov_b32_e32 v5, v0
	v_mov_b32_e32 v6, v0
	v_mov_b32_e32 v7, v0
	v_mov_b32_e32 v16, v0
	v_mov_b32_e32 v17, v0
	v_mov_b32_e32 v18, v0
	v_mov_b32_e32 v19, v0
	v_mov_b32_e32 v20, v0
	v_mov_b32_e32 v21, v0
	v_mov_b32_e32 v22, v0
	v_mov_b32_e32 v23, v0
	v_mov_b32_e32 v32, v0
	v_mov_b32_e32 v33, v0
	v_mov_b32_e32 v34, v0
	v_mov_b32_e32 v35, v0
	v_mov_b32_e32 v36, v0
	v_mov_b32_e32 v37, v0
	v_mov_b32_e32 v38, v0
	v_mov_b32_e32 v39, v0
	v_mov_b32_e32 v48, v0
	v_mov_b32_e32 v49, v0
	v_mov_b32_e32 v50, v0
	v_mov_b32_e32 v51, v0
	v_mov_b32_e32 v52, v0
	v_mov_b32_e32 v53, v0
	v_mov_b32_e32 v54, v0
	v_mov_b32_e32 v55, v0
	v_mov_b32_e32 v8, v0
	v_mov_b32_e32 v9, v0
	v_mov_b32_e32 v10, v0
	v_mov_b32_e32 v11, v0
	v_mov_b32_e32 v12, v0
	v_mov_b32_e32 v13, v0
	v_mov_b32_e32 v14, v0
	v_mov_b32_e32 v15, v0
	v_mov_b32_e32 v24, v0
	v_mov_b32_e32 v25, v0
	v_mov_b32_e32 v26, v0
	v_mov_b32_e32 v27, v0
	v_mov_b32_e32 v28, v0
	v_mov_b32_e32 v29, v0
	v_mov_b32_e32 v30, v0
	v_mov_b32_e32 v31, v0
	v_mov_b32_e32 v40, v0
	v_mov_b32_e32 v41, v0
	v_mov_b32_e32 v42, v0
	v_mov_b32_e32 v43, v0
	v_mov_b32_e32 v44, v0
	v_mov_b32_e32 v45, v0
	v_mov_b32_e32 v46, v0
	v_mov_b32_e32 v47, v0
	v_mov_b32_e32 v56, v0
	v_mov_b32_e32 v57, v0
	v_mov_b32_e32 v58, v0
	v_mov_b32_e32 v59, v0
	v_mov_b32_e32 v60, v0
	v_mov_b32_e32 v61, v0
	v_mov_b32_e32 v62, v0
	v_mov_b32_e32 v63, v0
	v_mov_b32_e32 v64, v0
	v_mov_b32_e32 v65, v0
	v_mov_b32_e32 v66, v0
	v_mov_b32_e32 v67, v0
	v_mov_b32_e32 v68, v0
	v_mov_b32_e32 v69, v0
	v_mov_b32_e32 v70, v0
	v_mov_b32_e32 v71, v0
	v_mov_b32_e32 v80, v0
	v_mov_b32_e32 v81, v0
	v_mov_b32_e32 v82, v0
	v_mov_b32_e32 v83, v0
	v_mov_b32_e32 v84, v0
	v_mov_b32_e32 v85, v0
	v_mov_b32_e32 v86, v0
	v_mov_b32_e32 v87, v0
	v_mov_b32_e32 v96, v0
	v_mov_b32_e32 v97, v0
	v_mov_b32_e32 v98, v0
	v_mov_b32_e32 v99, v0
	v_mov_b32_e32 v100, v0
	v_mov_b32_e32 v101, v0
	v_mov_b32_e32 v102, v0
	v_mov_b32_e32 v103, v0
	v_mov_b32_e32 v112, v0
	v_mov_b32_e32 v113, v0
	v_mov_b32_e32 v114, v0
	v_mov_b32_e32 v115, v0
	v_mov_b32_e32 v116, v0
	v_mov_b32_e32 v117, v0
	v_mov_b32_e32 v118, v0
	v_mov_b32_e32 v119, v0
	v_mov_b32_e32 v72, v0
	v_mov_b32_e32 v73, v0
	v_mov_b32_e32 v74, v0
	v_mov_b32_e32 v75, v0
	v_mov_b32_e32 v76, v0
	v_mov_b32_e32 v77, v0
	v_mov_b32_e32 v78, v0
	v_mov_b32_e32 v79, v0
	v_mov_b32_e32 v88, v0
	v_mov_b32_e32 v89, v0
	v_mov_b32_e32 v90, v0
	v_mov_b32_e32 v91, v0
	v_mov_b32_e32 v92, v0
	v_mov_b32_e32 v93, v0
	v_mov_b32_e32 v94, v0
	v_mov_b32_e32 v95, v0
	v_mov_b32_e32 v104, v0
	v_mov_b32_e32 v105, v0
	v_mov_b32_e32 v106, v0
	v_mov_b32_e32 v107, v0
	v_mov_b32_e32 v108, v0
	v_mov_b32_e32 v109, v0
	v_mov_b32_e32 v110, v0
	v_mov_b32_e32 v111, v0
	v_mov_b32_e32 v120, v0
	v_mov_b32_e32 v121, v0
	v_mov_b32_e32 v122, v0
	v_mov_b32_e32 v123, v0
	v_mov_b32_e32 v124, v0
	v_mov_b32_e32 v125, v0
	v_mov_b32_e32 v126, v0
	v_mov_b32_e32 v127, v0
	.p2alignl 6, 3212836864

.LBB0_1965:
	s_and_b64 vcc, exec, s[40:41]
	s_cbranch_vccnz .LBB0_1973
	s_add_u32 s24, s24, 0x40080
	s_addc_u32 s25, s25, 0
	s_add_u32 s9, s26, 0x100
	s_addc_u32 s11, s27, 0
	s_mov_b32 s26, 0
	v_mov_b32_e32 v0, 0
	v_mov_b32_e32 v1, 0
	v_mov_b32_e32 v2, 0
	v_mov_b32_e32 v3, 0
	v_mov_b32_e32 v8, 0
	v_mov_b32_e32 v9, 0
	v_mov_b32_e32 v10, 0
	v_mov_b32_e32 v11, 0
	v_mov_b32_e32 v16, 0
	v_mov_b32_e32 v17, 0
	v_mov_b32_e32 v18, 0
	v_mov_b32_e32 v19, 0
	v_mov_b32_e32 v24, 0
	v_mov_b32_e32 v25, 0
	v_mov_b32_e32 v26, 0
	v_mov_b32_e32 v27, 0
	v_mov_b32_e32 v32, 0
	v_mov_b32_e32 v33, 0
	v_mov_b32_e32 v34, 0
	v_mov_b32_e32 v35, 0
	v_mov_b32_e32 v40, 0
	v_mov_b32_e32 v41, 0
	v_mov_b32_e32 v42, 0
	v_mov_b32_e32 v43, 0
	v_mov_b32_e32 v64, 0
	v_mov_b32_e32 v65, 0
	v_mov_b32_e32 v66, 0
	v_mov_b32_e32 v67, 0
	v_mov_b32_e32 v72, 0
	v_mov_b32_e32 v73, 0
	v_mov_b32_e32 v74, 0
	v_mov_b32_e32 v75, 0
	v_mov_b32_e32 v4, 0
	v_mov_b32_e32 v5, 0
	v_mov_b32_e32 v6, 0
	v_mov_b32_e32 v7, 0
	v_mov_b32_e32 v12, 0
	v_mov_b32_e32 v13, 0
	v_mov_b32_e32 v14, 0
	v_mov_b32_e32 v15, 0
	v_mov_b32_e32 v20, 0
	v_mov_b32_e32 v21, 0
	v_mov_b32_e32 v22, 0
	v_mov_b32_e32 v23, 0
	v_mov_b32_e32 v28, 0
	v_mov_b32_e32 v29, 0
	v_mov_b32_e32 v30, 0
	v_mov_b32_e32 v31, 0
	v_mov_b32_e32 v36, 0
	v_mov_b32_e32 v37, 0
	v_mov_b32_e32 v38, 0
	v_mov_b32_e32 v39, 0
	v_mov_b32_e32 v44, 0
	v_mov_b32_e32 v45, 0
	v_mov_b32_e32 v46, 0
	v_mov_b32_e32 v47, 0
	v_mov_b32_e32 v68, 0
	v_mov_b32_e32 v69, 0
	v_mov_b32_e32 v70, 0
	v_mov_b32_e32 v71, 0
	v_mov_b32_e32 v76, 0
	v_mov_b32_e32 v77, 0
	v_mov_b32_e32 v78, 0
	v_mov_b32_e32 v79, 0
	v_mov_b32_e32 v80, 0
	v_mov_b32_e32 v81, 0
	v_mov_b32_e32 v82, 0
	v_mov_b32_e32 v83, 0
	v_mov_b32_e32 v88, 0
	v_mov_b32_e32 v89, 0
	v_mov_b32_e32 v90, 0
	v_mov_b32_e32 v91, 0
	s_waitcnt vmcnt(0)
	v_mov_b32_e32 v96, 0
	v_mov_b32_e32 v97, 0
	v_mov_b32_e32 v98, 0
	v_mov_b32_e32 v99, 0
	v_mov_b32_e32 v104, 0
	v_mov_b32_e32 v105, 0
	v_mov_b32_e32 v106, 0
	v_mov_b32_e32 v107, 0
	v_mov_b32_e32 v112, 0
	v_mov_b32_e32 v113, 0
	v_mov_b32_e32 v114, 0
	v_mov_b32_e32 v115, 0
	v_mov_b32_e32 v120, 0
	v_mov_b32_e32 v121, 0
	v_mov_b32_e32 v122, 0
	v_mov_b32_e32 v123, 0
	v_mov_b32_e32 v128, 0
	v_mov_b32_e32 v129, 0
	v_mov_b32_e32 v130, 0
	v_mov_b32_e32 v131, 0
	v_mov_b32_e32 v136, 0
	v_mov_b32_e32 v137, 0
	v_mov_b32_e32 v138, 0
	v_mov_b32_e32 v139, 0
	v_mov_b32_e32 v84, 0
	v_mov_b32_e32 v85, 0
	v_mov_b32_e32 v86, 0
	v_mov_b32_e32 v87, 0
	v_mov_b32_e32 v92, 0
	v_mov_b32_e32 v93, 0
	v_mov_b32_e32 v94, 0
	v_mov_b32_e32 v95, 0
	v_mov_b32_e32 v100, 0
	v_mov_b32_e32 v101, 0
	v_mov_b32_e32 v102, 0
	v_mov_b32_e32 v103, 0
	v_mov_b32_e32 v108, 0
	v_mov_b32_e32 v109, 0
	v_mov_b32_e32 v110, 0
	v_mov_b32_e32 v111, 0
	v_mov_b32_e32 v116, 0
	v_mov_b32_e32 v117, 0
	v_mov_b32_e32 v118, 0
	v_mov_b32_e32 v119, 0
	v_mov_b32_e32 v124, 0
	v_mov_b32_e32 v125, 0
	v_mov_b32_e32 v126, 0
	v_mov_b32_e32 v127, 0
	v_mov_b32_e32 v132, 0
	v_mov_b32_e32 v133, 0
	v_mov_b32_e32 v134, 0
	v_mov_b32_e32 v135, 0
	v_mov_b32_e32 v140, 0
	v_mov_b32_e32 v141, 0
	v_mov_b32_e32 v142, 0
	v_mov_b32_e32 v143, 0
	.p2alignl 6, 3212836864

.LBB0_2042:
	s_andn2_b64 vcc, exec, s[10:11]
	s_cbranch_vccnz .LBB0_2066
	s_add_u32 s43, s26, 0x100
	v_mov_b32_e32 v0, 0
	s_addc_u32 s44, s27, 0
	s_mov_b32 s28, 0
	s_waitcnt lgkmcnt(0)
	v_mov_b32_e32 v1, v0
	v_mov_b32_e32 v2, v0
	v_mov_b32_e32 v3, v0
	v_mov_b32_e32 v4, v0
	v_mov_b32_e32 v5, v0
	v_mov_b32_e32 v6, v0
	v_mov_b32_e32 v7, v0
	v_mov_b32_e32 v8, v0
	v_mov_b32_e32 v9, v0
	v_mov_b32_e32 v10, v0
	v_mov_b32_e32 v11, v0
	v_mov_b32_e32 v12, v0
	v_mov_b32_e32 v13, v0
	v_mov_b32_e32 v14, v0
	v_mov_b32_e32 v15, v0
	v_mov_b32_e32 v20, v0
	v_mov_b32_e32 v21, v0
	v_mov_b32_e32 v22, v0
	v_mov_b32_e32 v23, v0
	v_mov_b32_e32 v28, v0
	v_mov_b32_e32 v29, v0
	v_mov_b32_e32 v30, v0
	v_mov_b32_e32 v31, v0
	v_mov_b32_e32 v36, v0
	v_mov_b32_e32 v37, v0
	v_mov_b32_e32 v38, v0
	v_mov_b32_e32 v39, v0
	v_mov_b32_e32 v44, v0
	v_mov_b32_e32 v45, v0
	v_mov_b32_e32 v46, v0
	v_mov_b32_e32 v47, v0
	v_mov_b32_e32 v16, v0
	v_mov_b32_e32 v17, v0
	v_mov_b32_e32 v18, v0
	v_mov_b32_e32 v19, v0
	v_mov_b32_e32 v24, v0
	v_mov_b32_e32 v25, v0
	v_mov_b32_e32 v26, v0
	v_mov_b32_e32 v27, v0
	v_mov_b32_e32 v32, v0
	v_mov_b32_e32 v33, v0
	v_mov_b32_e32 v34, v0
	v_mov_b32_e32 v35, v0
	v_mov_b32_e32 v40, v0
	v_mov_b32_e32 v41, v0
	v_mov_b32_e32 v42, v0
	v_mov_b32_e32 v43, v0
	v_mov_b32_e32 v48, v0
	v_mov_b32_e32 v49, v0
	v_mov_b32_e32 v50, v0
	v_mov_b32_e32 v51, v0
	v_mov_b32_e32 v52, v0
	v_mov_b32_e32 v53, v0
	v_mov_b32_e32 v54, v0
	v_mov_b32_e32 v55, v0
	v_mov_b32_e32 v56, v0
	v_mov_b32_e32 v57, v0
	v_mov_b32_e32 v58, v0
	v_mov_b32_e32 v59, v0
	v_mov_b32_e32 v60, v0
	v_mov_b32_e32 v61, v0
	v_mov_b32_e32 v62, v0
	v_mov_b32_e32 v63, v0
	v_mov_b32_e32 v64, v0
	v_mov_b32_e32 v65, v0
	v_mov_b32_e32 v66, v0
	v_mov_b32_e32 v67, v0
	v_mov_b32_e32 v68, v0
	v_mov_b32_e32 v69, v0
	v_mov_b32_e32 v70, v0
	v_mov_b32_e32 v71, v0
	v_mov_b32_e32 v72, v0
	v_mov_b32_e32 v73, v0
	v_mov_b32_e32 v74, v0
	v_mov_b32_e32 v75, v0
	v_mov_b32_e32 v76, v0
	v_mov_b32_e32 v77, v0
	v_mov_b32_e32 v78, v0
	v_mov_b32_e32 v79, v0
	v_mov_b32_e32 v84, v0
	v_mov_b32_e32 v85, v0
	v_mov_b32_e32 v86, v0
	v_mov_b32_e32 v87, v0
	v_mov_b32_e32 v92, v0
	v_mov_b32_e32 v93, v0
	v_mov_b32_e32 v94, v0
	v_mov_b32_e32 v95, v0
	v_mov_b32_e32 v100, v0
	v_mov_b32_e32 v101, v0
	v_mov_b32_e32 v102, v0
	v_mov_b32_e32 v103, v0
	v_mov_b32_e32 v108, v0
	v_mov_b32_e32 v109, v0
	v_mov_b32_e32 v110, v0
	v_mov_b32_e32 v111, v0
	v_mov_b32_e32 v80, v0
	v_mov_b32_e32 v81, v0
	v_mov_b32_e32 v82, v0
	v_mov_b32_e32 v83, v0
	v_mov_b32_e32 v88, v0
	v_mov_b32_e32 v89, v0
	v_mov_b32_e32 v90, v0
	v_mov_b32_e32 v91, v0
	v_mov_b32_e32 v96, v0
	v_mov_b32_e32 v97, v0
	v_mov_b32_e32 v98, v0
	v_mov_b32_e32 v99, v0
	v_mov_b32_e32 v104, v0
	v_mov_b32_e32 v105, v0
	v_mov_b32_e32 v106, v0
	v_mov_b32_e32 v107, v0
	v_mov_b32_e32 v112, v0
	v_mov_b32_e32 v113, v0
	v_mov_b32_e32 v114, v0
	v_mov_b32_e32 v115, v0
	v_mov_b32_e32 v116, v0
	v_mov_b32_e32 v117, v0
	v_mov_b32_e32 v118, v0
	v_mov_b32_e32 v119, v0
	v_mov_b32_e32 v120, v0
	v_mov_b32_e32 v121, v0
	v_mov_b32_e32 v122, v0
	v_mov_b32_e32 v123, v0
	v_mov_b32_e32 v124, v0
	v_mov_b32_e32 v125, v0
	v_mov_b32_e32 v126, v0
	v_mov_b32_e32 v127, v0
	.p2alignl 6, 3212836864
